# epilogue de-serialisation, step 2: 11 of the attention epilogue's weight slices requested one barrier segment earlier (behind the tail's second barrier)
# speedup vs baseline: 1.0051x; 1.0051x over previous
; #define LAS __attribute__((address_space(3)))
; #define PG8_WAIT_V(n) asm volatile("s_waitcnt vmcnt(" #n ")" ::: "memory")
; #define PG8_BAR __builtin_amdgcn_s_barrier()
; #define MFMA32(a, b, c) __builtin_amdgcn_mfma_f32_32x32x16_bf16((a), (b), (c), 0, 0, 0)
; DI void attn_item(const Params& p, const int item) {
;     ...
;   PG8_WAIT_V(0); PG8_BAR;
;   {
;     const LAS unsigned char* vb = lds + m0 * 16384;
;     if ((nT - 1 == tL && tL > 0) || nT - 1 == tR) {
;       const float f = nT - 1 == tR ? fR : fL;
; #pragma unroll
;       for (int db = 0; db < 4; ++db)
; #pragma unroll
;         for (int i = 0; i < 16; ++i) O[db][i] *= f;
;     }
; #pragma unroll
;     for (int db = 0; db < 4; ++db)
; #pragma unroll
;       for (int s = 0; s < 4; ++s) { const bf16x8 vf = *(const LAS bf16x8*)(vb + db * 4096 + voff[s]); O[db] = MFMA32(vf, pf[s], O[db]); }
;   }
;     ...
;   PG8_WAIT_V(0); PG8_BAR;
;   lsum += __shfl_xor(lsum, 32);
;   const float sc = (c ? lam : 1.f) / lsum;
;   float* ex = (float*)shm_raw;
;   if (c == 1) {
; #pragma unroll
;     for (int db = 0; db < 4; ++db)
; #pragma unroll
;       for (int i = 0; i < 16; ++i) ex[(qs * 128 + 32 * db + (i & 3) + 8 * (i >> 2) + 4 * hl) * 32 + r] = O[db][i] * sc;
.LBB0_995:
	s_lshl_b32 s0, s26, 14
	s_add_i32 s0, s0, 0
	v_add_u32_e32 v84, s0, v228
	s_waitcnt vmcnt(0)
	s_barrier
	ds_read_b128 v[64:67], v84 offset:49152
	ds_read_b128 v[68:71], v84 offset:53248
	v_add_u32_e32 v85, s0, v227
	v_add_u32_e32 v86, s0, v226
	v_add_u32_e32 v87, s0, v225
	v_cmp_lt_i32_e32 vcc, v206, v205
	s_cmpk_lt_u32 s13, 0x100
	s_waitcnt lgkmcnt(1)
	v_mfma_f32_32x32x16_bf16 v[48:63], v[64:67], v[120:123], v[48:63]
	ds_read_b128 v[64:67], v85 offset:49152
	ds_read_b128 v[72:75], v85 offset:53248
	s_cselect_b64 s[0:1], -1, 0
	s_cmp_eq_u32 s16, 1
	ds_read_b128 v[76:79], v86 offset:53248
	s_waitcnt lgkmcnt(2)
	v_mfma_f32_32x32x16_bf16 v[48:63], v[64:67], v[112:115], v[48:63]
	ds_read_b128 v[64:67], v86 offset:49152
	s_waitcnt lgkmcnt(0)
	v_mfma_f32_32x32x16_bf16 v[48:63], v[64:67], v[124:127], v[48:63]
	ds_read_b128 v[64:67], v87 offset:49152
	ds_read_b128 v[80:83], v87 offset:53248
	v_mfma_f32_32x32x16_bf16 v[32:47], v[68:71], v[120:123], v[32:47]
	s_waitcnt lgkmcnt(1)
	v_mfma_f32_32x32x16_bf16 v[48:63], v[64:67], v[116:119], v[48:63]
	v_mfma_f32_32x32x16_bf16 v[32:47], v[72:75], v[112:115], v[32:47]
	ds_read_b128 v[64:67], v84 offset:57344
	ds_read_b128 v[70:73], v84 offset:61440
	s_waitcnt lgkmcnt(1)
	v_mfma_f32_32x32x16_bf16 v[16:31], v[64:67], v[120:123], v[16:31]
	v_mfma_f32_32x32x16_bf16 v[32:47], v[76:79], v[124:127], v[32:47]
	ds_read_b128 v[64:67], v85 offset:57344
	ds_read_b128 v[74:77], v85 offset:61440
	s_waitcnt lgkmcnt(1)
	v_mfma_f32_32x32x16_bf16 v[16:31], v[64:67], v[112:115], v[16:31]
	v_mfma_f32_32x32x16_bf16 v[32:47], v[80:83], v[116:119], v[32:47]
	ds_read_b128 v[64:67], v86 offset:57344
	ds_read_b128 v[78:81], v86 offset:61440
	v_mfma_f32_32x32x16_bf16 v[0:15], v[70:73], v[120:123], v[0:15]
	s_waitcnt lgkmcnt(1)
	v_mfma_f32_32x32x16_bf16 v[16:31], v[64:67], v[124:127], v[16:31]
	ds_read_b128 v[64:67], v87 offset:57344
	ds_read_b128 v[82:85], v87 offset:61440
	s_waitcnt vmcnt(0)
	s_barrier
	global_load_dwordx4 v[148:151], v192, s[72:73] offset:32
	global_load_dwordx4 v[152:155], v192, s[72:73] offset:64
	global_load_dwordx4 v[156:159], v192, s[72:73] offset:96
	global_load_dwordx4 v[160:163], v192, s[72:73] offset:128
	global_load_dwordx4 v[164:167], v192, s[72:73] offset:160
	global_load_dwordx4 v[168:171], v192, s[72:73] offset:192
	global_load_dwordx4 v[172:175], v192, s[72:73] offset:224
	global_load_dwordx4 v[176:179], v192, s[72:73] offset:256
	global_load_dwordx4 v[180:183], v192, s[72:73] offset:288
	global_load_dwordx4 v[184:187], v192, s[72:73] offset:320
	global_load_dwordx4 v[188:191], v192, s[72:73] offset:352
	v_mfma_f32_32x32x16_bf16 v[0:15], v[74:77], v[112:115], v[0:15]
	s_waitcnt lgkmcnt(1)
	v_mfma_f32_32x32x16_bf16 v[16:31], v[64:67], v[116:119], v[16:31]
	v_cndmask_b32_e32 v64, v204, v206, vcc
	v_lshlrev_b32_e32 v69, 2, v64
	ds_bpermute_b32 v64, v69, v231
	v_cndmask_b32_e64 v65, v200, 1.0, s[0:1]
	s_waitcnt lgkmcnt(0)
	v_add_f32_e32 v64, v231, v64
	v_mfma_f32_32x32x16_bf16 v[0:15], v[78:81], v[124:127], v[0:15]
	v_div_scale_f32 v66, s[4:5], v64, v64, v65
	v_rcp_f32_e32 v67, v66
	s_nop 0
	v_fma_f32 v68, -v66, v67, 1.0
	v_mfma_f32_32x32x16_bf16 v[0:15], v[82:85], v[116:119], v[0:15]
	v_fmac_f32_e32 v67, v68, v67
	v_div_scale_f32 v68, vcc, v65, v64, v65
	v_mul_f32_e32 v70, v68, v67
	v_fma_f32 v71, -v66, v70, v68
	v_fmac_f32_e32 v70, v71, v67
	v_fma_f32 v66, -v66, v70, v68
	v_div_fmas_f32 v66, v66, v67, v70
	v_div_fixup_f32 v68, v66, v64, v65
	v_lshlrev_b32_e32 v64, 2, v201
	v_lshl_add_u32 v65, v217, 9, 0
	s_cbranch_scc0 .LBB0_997
	s_lshl_b32 s4, s15, 14
	v_mul_f32_e32 v66, v48, v68
	v_add3_u32 v67, v65, v64, s4
	v_mul_f32_e32 v70, v49, v68
	ds_write2_b32 v67, v66, v70 offset1:32
	v_mul_f32_e32 v66, v50, v68
	v_mul_f32_e32 v70, v51, v68
	ds_write2_b32 v67, v66, v70 offset0:64 offset1:96
	v_mul_f32_e32 v66, v52, v68
	v_mul_f32_e32 v70, v53, v68
	v_add_u32_e32 v71, 0x400, v67
	ds_write2_b32 v71, v66, v70 offset1:32
	v_mul_f32_e32 v66, v54, v68
	v_mul_f32_e32 v70, v55, v68
	ds_write2_b32 v71, v66, v70 offset0:64 offset1:96
	v_mul_f32_e32 v66, v56, v68
	v_mul_f32_e32 v70, v57, v68
	v_add_u32_e32 v71, 0x800, v67
	ds_write2_b32 v71, v66, v70 offset1:32
	v_mul_f32_e32 v66, v58, v68
	v_mul_f32_e32 v70, v59, v68
	ds_write2_b32 v71, v66, v70 offset0:64 offset1:96
	v_mul_f32_e32 v66, v60, v68
	v_mul_f32_e32 v70, v61, v68
	v_add_u32_e32 v71, 0xc00, v67
	ds_write2_b32 v71, v66, v70 offset1:32
	v_mul_f32_e32 v66, v62, v68
	v_mul_f32_e32 v70, v63, v68
	ds_write2_b32 v71, v66, v70 offset0:64 offset1:96
	v_mul_f32_e32 v66, v32, v68
	v_mul_f32_e32 v70, v33, v68
	v_add_u32_e32 v71, 0x1000, v67
	ds_write2_b32 v71, v66, v70 offset1:32
	v_mul_f32_e32 v66, v34, v68
	v_mul_f32_e32 v70, v35, v68
	ds_write2_b32 v71, v66, v70 offset0:64 offset1:96
	v_mul_f32_e32 v66, v36, v68
	v_mul_f32_e32 v70, v37, v68
	v_add_u32_e32 v71, 0x1400, v67
	ds_write2_b32 v71, v66, v70 offset1:32
	v_mul_f32_e32 v66, v38, v68
	v_mul_f32_e32 v70, v39, v68
	ds_write2_b32 v71, v66, v70 offset0:64 offset1:96
	v_mul_f32_e32 v66, v40, v68
	v_mul_f32_e32 v70, v41, v68
	v_add_u32_e32 v71, 0x1800, v67
	ds_write2_b32 v71, v66, v70 offset1:32
	v_mul_f32_e32 v66, v42, v68
	v_mul_f32_e32 v70, v43, v68
	ds_write2_b32 v71, v66, v70 offset0:64 offset1:96
	v_mul_f32_e32 v66, v44, v68
	v_mul_f32_e32 v70, v45, v68
	v_add_u32_e32 v71, 0x1c00, v67
	ds_write2_b32 v71, v66, v70 offset1:32
	v_mul_f32_e32 v66, v46, v68
	v_mul_f32_e32 v70, v47, v68
	ds_write2_b32 v71, v66, v70 offset0:64 offset1:96
	v_mul_f32_e32 v66, v16, v68
	v_mul_f32_e32 v70, v17, v68
	v_add_u32_e32 v71, 0x2000, v67
	ds_write2_b32 v71, v66, v70 offset1:32
	v_mul_f32_e32 v66, v18, v68
; DI void attn_item(const Params& p, const int item) {
;     ...
;   if (c == 1) {
; #pragma unroll
;     for (int db = 0; db < 4; ++db)
; #pragma unroll
;       for (int i = 0; i < 16; ++i) ex[(qs * 128 + 32 * db + (i & 3) + 8 * (i >> 2) + 4 * hl) * 32 + r] = O[db][i] * sc;
;   }
;   __syncthreads();
;   if (c == 0) {
;     float ss = 0.f;
; #pragma unroll
;     for (int db = 0; db < 4; ++db)
; #pragma unroll
;       for (int i = 0; i < 16; ++i) { const float o = O[db][i] * sc - ex[(qs * 128 + 32 * db + (i & 3) + 8 * (i >> 2) + 4 * hl) * 32 + r]; O[db][i] = o; ss += o * o; }
	v_mul_f32_e32 v70, v19, v68
	ds_write2_b32 v71, v66, v70 offset0:64 offset1:96
	v_mul_f32_e32 v66, v20, v68
	v_mul_f32_e32 v70, v21, v68
	v_add_u32_e32 v71, 0x2400, v67
	ds_write2_b32 v71, v66, v70 offset1:32
	v_mul_f32_e32 v66, v22, v68
	v_mul_f32_e32 v70, v23, v68
	ds_write2_b32 v71, v66, v70 offset0:64 offset1:96
	v_mul_f32_e32 v66, v24, v68
	v_mul_f32_e32 v70, v25, v68
	v_add_u32_e32 v71, 0x2800, v67
	ds_write2_b32 v71, v66, v70 offset1:32
	v_mul_f32_e32 v66, v26, v68
	v_mul_f32_e32 v70, v27, v68
	ds_write2_b32 v71, v66, v70 offset0:64 offset1:96
	v_mul_f32_e32 v66, v28, v68
	v_mul_f32_e32 v70, v29, v68
	v_add_u32_e32 v71, 0x2c00, v67
	ds_write2_b32 v71, v66, v70 offset1:32
	v_mul_f32_e32 v66, v30, v68
	v_mul_f32_e32 v70, v31, v68
	ds_write2_b32 v71, v66, v70 offset0:64 offset1:96
	v_mul_f32_e32 v66, v0, v68
	v_mul_f32_e32 v70, v1, v68
	v_add_u32_e32 v71, 0x3000, v67
	ds_write2_b32 v71, v66, v70 offset1:32
	v_mul_f32_e32 v66, v2, v68
	v_mul_f32_e32 v70, v3, v68
	ds_write2_b32 v71, v66, v70 offset0:64 offset1:96
	v_mul_f32_e32 v66, v4, v68
	v_mul_f32_e32 v70, v5, v68
	v_add_u32_e32 v71, 0x3400, v67
	ds_write2_b32 v71, v66, v70 offset1:32
	v_mul_f32_e32 v66, v6, v68
	v_mul_f32_e32 v70, v7, v68
	ds_write2_b32 v71, v66, v70 offset0:64 offset1:96
	v_mul_f32_e32 v66, v8, v68
	v_mul_f32_e32 v70, v9, v68
	v_add_u32_e32 v71, 0x3800, v67
	ds_write2_b32 v71, v66, v70 offset1:32
	v_mul_f32_e32 v66, v10, v68
	v_mul_f32_e32 v70, v11, v68
	ds_write2_b32 v71, v66, v70 offset0:64 offset1:96
	v_mul_f32_e32 v66, v12, v68
	v_mul_f32_e32 v70, v13, v68
	v_add_u32_e32 v67, 0x3c00, v67
	ds_write2_b32 v67, v66, v70 offset1:32
	v_mul_f32_e32 v66, v14, v68
	v_mul_f32_e32 v70, v15, v68
	ds_write2_b32 v67, v66, v70 offset0:64 offset1:96
.LBB0_997:
	s_andn2_b64 vcc, exec, s[0:1]
	s_waitcnt vmcnt(0) lgkmcnt(0)
	s_barrier
	s_cbranch_vccnz .LBB0_999
	s_lshl_b32 s0, s14, 14
	v_add3_u32 v66, v65, v64, s0
	v_add_u32_e32 v64, 0x400, v66
	ds_read2_b32 v[72:73], v66 offset1:32
	ds_read2_b32 v[74:75], v66 offset0:64 offset1:96
	ds_read2_b32 v[76:77], v64 offset1:32
	ds_read2_b32 v[78:79], v64 offset0:64 offset1:96
	v_add_u32_e32 v64, 0x800, v66
	ds_read2_b32 v[80:81], v64 offset1:32
	ds_read2_b32 v[82:83], v64 offset0:64 offset1:96
	v_add_u32_e32 v64, 0xc00, v66
	ds_read2_b32 v[84:85], v64 offset1:32
	ds_read2_b32 v[86:87], v64 offset0:64 offset1:96
	v_add_u32_e32 v64, 0x1000, v66
	ds_read2_b32 v[88:89], v64 offset1:32
	ds_read2_b32 v[90:91], v64 offset0:64 offset1:96
	v_add_u32_e32 v64, 0x1400, v66
	ds_read2_b32 v[92:93], v64 offset1:32
	ds_read2_b32 v[94:95], v64 offset0:64 offset1:96
	v_add_u32_e32 v64, 0x1800, v66
	ds_read2_b32 v[96:97], v64 offset1:32
	ds_read2_b32 v[98:99], v64 offset0:64 offset1:96
	v_add_u32_e32 v64, 0x1c00, v66
	ds_read2_b32 v[100:101], v64 offset1:32
	ds_read2_b32 v[102:103], v64 offset0:64 offset1:96
	v_add_u32_e32 v64, 0x2000, v66
	ds_read2_b32 v[104:105], v64 offset1:32
	ds_read2_b32 v[106:107], v64 offset0:64 offset1:96
	v_add_u32_e32 v64, 0x2400, v66
	ds_read2_b32 v[108:109], v64 offset1:32
	ds_read2_b32 v[110:111], v64 offset0:64 offset1:96
	v_add_u32_e32 v64, 0x2800, v66
	ds_read2_b32 v[112:113], v64 offset1:32
	ds_read2_b32 v[114:115], v64 offset0:64 offset1:96
	v_add_u32_e32 v64, 0x2c00, v66
	ds_read2_b32 v[116:117], v64 offset1:32
	ds_read2_b32 v[118:119], v64 offset0:64 offset1:96
	v_add_u32_e32 v64, 0x3000, v66
	ds_read2_b32 v[120:121], v64 offset1:32
	ds_read2_b32 v[122:123], v64 offset0:64 offset1:96
	v_add_u32_e32 v64, 0x3400, v66
	v_add_u32_e32 v67, 0x3c00, v66
	ds_read2_b32 v[124:125], v64 offset1:32
	ds_read2_b32 v[126:127], v64 offset0:64 offset1:96
	ds_read2_b32 v[64:65], v67 offset1:32
	v_add_u32_e32 v70, 0x3800, v66
	ds_read2_b32 v[66:67], v67 offset0:64 offset1:96
	ds_read2_b32 v[128:129], v70 offset1:32
	ds_read2_b32 v[130:131], v70 offset0:64 offset1:96
	s_waitcnt lgkmcnt(14)
	v_pk_fma_f32 v[136:137], v[48:49], v[68:69], v[72:73] op_sel_hi:[1,0,1] neg_lo:[0,0,1] neg_hi:[0,0,1]
	v_pk_fma_f32 v[50:51], v[50:51], v[68:69], v[74:75] op_sel_hi:[1,0,1] neg_lo:[0,0,1] neg_hi:[0,0,1]
	v_pk_mul_f32 v[138:139], v[136:137], v[136:137]
	s_waitcnt lgkmcnt(3)
	v_pk_fma_f32 v[64:65], v[12:13], v[68:69], v[64:65] op_sel_hi:[1,0,1] neg_lo:[0,0,1] neg_hi:[0,0,1]
	s_waitcnt lgkmcnt(2)
; DI void attn_item(const Params& p, const int item) {
;     ...
;   if (c == 0) {
;     float ss = 0.f;
; #pragma unroll
;     for (int db = 0; db < 4; ++db)
; #pragma unroll
;       for (int i = 0; i < 16; ++i) { const float o = O[db][i] * sc - ex[(qs * 128 + 32 * db + (i & 3) + 8 * (i >> 2) + 4 * hl) * 32 + r]; O[db][i] = o; ss += o * o; }
;     ss += __shfl_xor(ss, 32);
;     const float rstd = rsqrtf(ss * (1.f / 128.f) + EPSN) * 0.8f;
;     bf16_t* dst = (bf16_t*)(p.ws + WS_OCAT) + (size_t)(T0 + qpos) * 1024 + h * 128;
; #pragma unroll
;     for (int db = 0; db < 4; ++db)
; #pragma unroll
;       for (int i4 = 0; i4 < 4; ++i4) {
;         const int d0 = 32 * db + 8 * i4 + 4 * hl;
;         const float4 w = *(const float4*)(p.diff_subln_w + d0);
	v_pk_fma_f32 v[66:67], v[14:15], v[68:69], v[66:67] op_sel_hi:[1,0,1] neg_lo:[0,0,1] neg_hi:[0,0,1]
	v_pk_mul_f32 v[74:75], v[50:51], v[50:51]
	global_load_dwordx4 v[12:15], v192, s[72:73]
	global_load_dwordx4 v[220:223], v192, s[72:73] offset:384
	global_load_dwordx4 v[224:227], v192, s[72:73] offset:416
	global_load_dwordx4 v[228:231], v192, s[72:73] offset:448
	global_load_dwordx4 v[232:235], v192, s[72:73] offset:480
	v_pk_fma_f32 v[72:73], v[54:55], v[68:69], v[78:79] op_sel_hi:[1,0,1] neg_lo:[0,0,1] neg_hi:[0,0,1]
	v_pk_fma_f32 v[76:77], v[52:53], v[68:69], v[76:77] op_sel_hi:[1,0,1] neg_lo:[0,0,1] neg_hi:[0,0,1]
	v_pk_fma_f32 v[58:59], v[58:59], v[68:69], v[82:83] op_sel_hi:[1,0,1] neg_lo:[0,0,1] neg_hi:[0,0,1]
	v_pk_fma_f32 v[80:81], v[56:57], v[68:69], v[80:81] op_sel_hi:[1,0,1] neg_lo:[0,0,1] neg_hi:[0,0,1]
	v_pk_fma_f32 v[54:55], v[62:63], v[68:69], v[86:87] op_sel_hi:[1,0,1] neg_lo:[0,0,1] neg_hi:[0,0,1]
	v_pk_fma_f32 v[84:85], v[60:61], v[68:69], v[84:85] op_sel_hi:[1,0,1] neg_lo:[0,0,1] neg_hi:[0,0,1]
	v_pk_fma_f32 v[52:53], v[34:35], v[68:69], v[90:91] op_sel_hi:[1,0,1] neg_lo:[0,0,1] neg_hi:[0,0,1]
	v_pk_fma_f32 v[88:89], v[32:33], v[68:69], v[88:89] op_sel_hi:[1,0,1] neg_lo:[0,0,1] neg_hi:[0,0,1]
	v_pk_fma_f32 v[48:49], v[38:39], v[68:69], v[94:95] op_sel_hi:[1,0,1] neg_lo:[0,0,1] neg_hi:[0,0,1]
	v_pk_fma_f32 v[60:61], v[36:37], v[68:69], v[92:93] op_sel_hi:[1,0,1] neg_lo:[0,0,1] neg_hi:[0,0,1]
	v_pk_fma_f32 v[38:39], v[42:43], v[68:69], v[98:99] op_sel_hi:[1,0,1] neg_lo:[0,0,1] neg_hi:[0,0,1]
	v_pk_fma_f32 v[56:57], v[40:41], v[68:69], v[96:97] op_sel_hi:[1,0,1] neg_lo:[0,0,1] neg_hi:[0,0,1]
	v_pk_fma_f32 v[34:35], v[46:47], v[68:69], v[102:103] op_sel_hi:[1,0,1] neg_lo:[0,0,1] neg_hi:[0,0,1]
	v_pk_fma_f32 v[44:45], v[44:45], v[68:69], v[100:101] op_sel_hi:[1,0,1] neg_lo:[0,0,1] neg_hi:[0,0,1]
	v_pk_fma_f32 v[32:33], v[18:19], v[68:69], v[106:107] op_sel_hi:[1,0,1] neg_lo:[0,0,1] neg_hi:[0,0,1]
	v_pk_fma_f32 v[42:43], v[16:17], v[68:69], v[104:105] op_sel_hi:[1,0,1] neg_lo:[0,0,1] neg_hi:[0,0,1]
	v_pk_fma_f32 v[22:23], v[22:23], v[68:69], v[110:111] op_sel_hi:[1,0,1] neg_lo:[0,0,1] neg_hi:[0,0,1]
	v_pk_fma_f32 v[40:41], v[20:21], v[68:69], v[108:109] op_sel_hi:[1,0,1] neg_lo:[0,0,1] neg_hi:[0,0,1]
	v_pk_fma_f32 v[20:21], v[26:27], v[68:69], v[114:115] op_sel_hi:[1,0,1] neg_lo:[0,0,1] neg_hi:[0,0,1]
	v_pk_fma_f32 v[36:37], v[24:25], v[68:69], v[112:113] op_sel_hi:[1,0,1] neg_lo:[0,0,1] neg_hi:[0,0,1]
	v_pk_fma_f32 v[18:19], v[30:31], v[68:69], v[118:119] op_sel_hi:[1,0,1] neg_lo:[0,0,1] neg_hi:[0,0,1]
	v_pk_fma_f32 v[26:27], v[28:29], v[68:69], v[116:117] op_sel_hi:[1,0,1] neg_lo:[0,0,1] neg_hi:[0,0,1]
	v_pk_fma_f32 v[16:17], v[2:3], v[68:69], v[122:123] op_sel_hi:[1,0,1] neg_lo:[0,0,1] neg_hi:[0,0,1]
	v_pk_fma_f32 v[24:25], v[0:1], v[68:69], v[120:121] op_sel_hi:[1,0,1] neg_lo:[0,0,1] neg_hi:[0,0,1]
	v_pk_fma_f32 v[2:3], v[6:7], v[68:69], v[126:127] op_sel_hi:[1,0,1] neg_lo:[0,0,1] neg_hi:[0,0,1]
	v_pk_fma_f32 v[6:7], v[4:5], v[68:69], v[124:125] op_sel_hi:[1,0,1] neg_lo:[0,0,1] neg_hi:[0,0,1]
	s_waitcnt lgkmcnt(0)
	v_pk_fma_f32 v[0:1], v[10:11], v[68:69], v[130:131] op_sel_hi:[1,0,1] neg_lo:[0,0,1] neg_hi:[0,0,1]
	v_pk_fma_f32 v[4:5], v[8:9], v[68:69], v[128:129] op_sel_hi:[1,0,1] neg_lo:[0,0,1] neg_hi:[0,0,1]
	v_add_f32_e32 v68, v138, v139
	v_add_f32_e32 v68, v68, v74
	v_pk_mul_f32 v[140:141], v[76:77], v[76:77]
	v_add_f32_e32 v68, v68, v75
	v_add_f32_e32 v68, v68, v140
	v_pk_mul_f32 v[78:79], v[72:73], v[72:73]
	v_add_f32_e32 v68, v68, v141
	v_add_f32_e32 v68, v68, v78
	v_pk_mul_f32 v[142:143], v[80:81], v[80:81]
	v_add_f32_e32 v68, v68, v79
	v_add_f32_e32 v68, v68, v142
	v_pk_mul_f32 v[82:83], v[58:59], v[58:59]
	v_add_f32_e32 v68, v68, v143
	v_add_f32_e32 v68, v68, v82
	v_pk_mul_f32 v[86:87], v[84:85], v[84:85]
	v_add_f32_e32 v68, v68, v83
	v_add_f32_e32 v68, v68, v86
	v_pk_mul_f32 v[62:63], v[54:55], v[54:55]
	v_add_f32_e32 v68, v68, v87
	v_add_f32_e32 v62, v68, v62
	v_pk_mul_f32 v[144:145], v[88:89], v[88:89]
	v_add_f32_e32 v62, v62, v63
	v_add_f32_e32 v62, v62, v144
	v_pk_mul_f32 v[90:91], v[52:53], v[52:53]
	v_add_f32_e32 v62, v62, v145
	v_add_f32_e32 v62, v62, v90
	v_pk_mul_f32 v[92:93], v[60:61], v[60:61]
	v_add_f32_e32 v62, v62, v91
	v_add_f32_e32 v62, v62, v92
	v_pk_mul_f32 v[94:95], v[48:49], v[48:49]
	v_add_f32_e32 v62, v62, v93
	v_add_f32_e32 v62, v62, v94
	v_pk_mul_f32 v[96:97], v[56:57], v[56:57]
	v_add_f32_e32 v62, v62, v95
	v_add_f32_e32 v62, v62, v96
	v_pk_mul_f32 v[98:99], v[38:39], v[38:39]
	v_add_f32_e32 v62, v62, v97
	v_add_f32_e32 v62, v62, v98
	v_pk_mul_f32 v[100:101], v[44:45], v[44:45]
	v_add_f32_e32 v62, v62, v99
	v_add_f32_e32 v62, v62, v100
	v_pk_mul_f32 v[46:47], v[34:35], v[34:35]
	v_add_f32_e32 v62, v62, v101
	v_add_f32_e32 v46, v62, v46
	v_pk_mul_f32 v[104:105], v[42:43], v[42:43]
	v_add_f32_e32 v46, v46, v47
	v_add_f32_e32 v46, v46, v104
	v_pk_mul_f32 v[102:103], v[32:33], v[32:33]
	v_add_f32_e32 v46, v46, v105
	v_add_f32_e32 v46, v46, v102
	v_pk_mul_f32 v[108:109], v[40:41], v[40:41]
	v_add_f32_e32 v46, v46, v103
	v_add_f32_e32 v46, v46, v108
	v_pk_mul_f32 v[106:107], v[22:23], v[22:23]
	v_add_f32_e32 v46, v46, v109
	v_add_f32_e32 v46, v46, v106
	v_pk_mul_f32 v[112:113], v[36:37], v[36:37]
	v_add_f32_e32 v46, v46, v107
	v_add_f32_e32 v46, v46, v112
	v_pk_mul_f32 v[110:111], v[20:21], v[20:21]
	v_add_f32_e32 v46, v46, v113
	v_add_f32_e32 v46, v46, v110
	v_pk_mul_f32 v[28:29], v[26:27], v[26:27]
	v_add_f32_e32 v46, v46, v111
	v_add_f32_e32 v28, v46, v28
	v_pk_mul_f32 v[30:31], v[18:19], v[18:19]
	v_add_f32_e32 v28, v28, v29
	v_add_f32_e32 v28, v28, v30
	v_pk_mul_f32 v[116:117], v[24:25], v[24:25]
	v_add_f32_e32 v28, v28, v31
	v_add_f32_e32 v28, v28, v116
	v_pk_mul_f32 v[114:115], v[16:17], v[16:17]
	v_add_f32_e32 v28, v28, v117
	v_add_f32_e32 v28, v28, v114
	v_pk_mul_f32 v[120:121], v[6:7], v[6:7]
	v_add_f32_e32 v28, v28, v115
	v_add_f32_e32 v28, v28, v120
	v_pk_mul_f32 v[118:119], v[2:3], v[2:3]
	v_add_f32_e32 v28, v28, v121
	v_add_f32_e32 v28, v28, v118
	v_pk_mul_f32 v[8:9], v[4:5], v[4:5]
	v_add_f32_e32 v28, v28, v119
	v_add_f32_e32 v8, v28, v8
	v_pk_mul_f32 v[10:11], v[0:1], v[0:1]
	v_add_f32_e32 v8, v8, v9
	v_add_f32_e32 v8, v8, v10
	v_pk_mul_f32 v[70:71], v[64:65], v[64:65]
	v_add_f32_e32 v8, v8, v11
	v_add_f32_e32 v8, v8, v70
	v_pk_mul_f32 v[132:133], v[66:67], v[66:67]
	v_add_f32_e32 v8, v8, v71
	v_add_f32_e32 v8, v8, v132
	v_add_f32_e32 v10, v8, v133
	ds_bpermute_b32 v11, v69, v10
	s_mov_b32 s0, 0x800000
	v_add_u32_e32 v134, s6, v199
	v_mov_b32_e32 v135, v193
	v_lshlrev_b64 v[8:9], 11, v[134:135]
	s_waitcnt lgkmcnt(0)
; DI unsigned pk_bf16(float lo, float hi) { f32x2 v = {lo, hi}; return __builtin_bit_cast(unsigned, __builtin_convertvector(v, bf16x2_t)); }
; DI void attn_item(const Params& p, const int item) {
;     ...
;     ss += __shfl_xor(ss, 32);
;     const float rstd = rsqrtf(ss * (1.f / 128.f) + EPSN) * 0.8f;
;     bf16_t* dst = (bf16_t*)(p.ws + WS_OCAT) + (size_t)(T0 + qpos) * 1024 + h * 128;
; #pragma unroll
;     for (int db = 0; db < 4; ++db)
; #pragma unroll
;       for (int i4 = 0; i4 < 4; ++i4) {
;         const int d0 = 32 * db + 8 * i4 + 4 * hl;
;         const float4 w = *(const float4*)(p.diff_subln_w + d0);
;         uint2 q; q.x = pk_bf16(O[db][4 * i4] * rstd * w.x, O[db][4 * i4 + 1] * rstd * w.y); q.y = pk_bf16(O[db][4 * i4 + 2] * rstd * w.z, O[db][4 * i4 + 3] * rstd * w.w);
;         *(uint2*)(dst + d0) = q;
;       }
	v_add_f32_e32 v10, v10, v11
	v_fmamk_f32 v10, v10, 0x3c000000, v212
	v_mul_f32_e32 v11, 0x4b800000, v10
	v_cmp_gt_f32_e32 vcc, s0, v10
	v_lshl_add_u64 v[8:9], s[68:69], 0, v[8:9]
	s_lshl_b32 s70, s3, 8
	v_cndmask_b32_e32 v10, v10, v11, vcc
	v_rsq_f32_e32 v10, v10
	v_lshl_add_u64 v[8:9], v[8:9], 0, s[70:71]
	v_mov_b32_e32 v199, v193
	v_lshl_add_u64 v[28:29], v[8:9], 0, v[198:199]
	v_mul_f32_e32 v8, 0x45800000, v10
	v_cndmask_b32_e32 v8, v10, v8, vcc
	v_mul_f32_e32 v30, 0x3f4ccccd, v8
	s_waitcnt vmcnt(0)
	v_pk_mul_f32 v[244:245], v[136:137], v[30:31] op_sel_hi:[1,0]
	v_pk_mul_f32 v[246:247], v[50:51], v[30:31] op_sel_hi:[1,0]
	v_pk_mul_f32 v[244:245], v[12:13], v[244:245]
	v_pk_mul_f32 v[246:247], v[14:15], v[246:247]
	v_cvt_pk_bf16_f32 v248, v244, v245
	v_cvt_pk_bf16_f32 v249, v246, v247
	global_store_dwordx2 v[28:29], v[248:249], off
	v_pk_mul_f32 v[244:245], v[76:77], v[30:31] op_sel_hi:[1,0]
	v_pk_mul_f32 v[246:247], v[72:73], v[30:31] op_sel_hi:[1,0]
	v_pk_mul_f32 v[244:245], v[148:149], v[244:245]
	v_pk_mul_f32 v[246:247], v[150:151], v[246:247]
	v_cvt_pk_bf16_f32 v250, v244, v245
	v_cvt_pk_bf16_f32 v251, v246, v247
	global_store_dwordx2 v[28:29], v[250:251], off offset:16
	v_pk_mul_f32 v[244:245], v[80:81], v[30:31] op_sel_hi:[1,0]
	v_pk_mul_f32 v[246:247], v[58:59], v[30:31] op_sel_hi:[1,0]
	v_pk_mul_f32 v[244:245], v[152:153], v[244:245]
	v_pk_mul_f32 v[246:247], v[154:155], v[246:247]
	v_cvt_pk_bf16_f32 v248, v244, v245
	v_cvt_pk_bf16_f32 v249, v246, v247
	global_store_dwordx2 v[28:29], v[248:249], off offset:32
	v_pk_mul_f32 v[244:245], v[84:85], v[30:31] op_sel_hi:[1,0]
	v_pk_mul_f32 v[246:247], v[54:55], v[30:31] op_sel_hi:[1,0]
	v_pk_mul_f32 v[244:245], v[156:157], v[244:245]
	v_pk_mul_f32 v[246:247], v[158:159], v[246:247]
	v_cvt_pk_bf16_f32 v250, v244, v245
	v_cvt_pk_bf16_f32 v251, v246, v247
	global_store_dwordx2 v[28:29], v[250:251], off offset:48
	v_pk_mul_f32 v[244:245], v[88:89], v[30:31] op_sel_hi:[1,0]
	v_pk_mul_f32 v[246:247], v[52:53], v[30:31] op_sel_hi:[1,0]
	v_pk_mul_f32 v[244:245], v[160:161], v[244:245]
	v_pk_mul_f32 v[246:247], v[162:163], v[246:247]
	v_cvt_pk_bf16_f32 v248, v244, v245
	v_cvt_pk_bf16_f32 v249, v246, v247
	global_store_dwordx2 v[28:29], v[248:249], off offset:64
	v_pk_mul_f32 v[244:245], v[60:61], v[30:31] op_sel_hi:[1,0]
	v_pk_mul_f32 v[246:247], v[48:49], v[30:31] op_sel_hi:[1,0]
	v_pk_mul_f32 v[244:245], v[164:165], v[244:245]
	v_pk_mul_f32 v[246:247], v[166:167], v[246:247]
	v_cvt_pk_bf16_f32 v250, v244, v245
	v_cvt_pk_bf16_f32 v251, v246, v247
	global_store_dwordx2 v[28:29], v[250:251], off offset:80
	v_pk_mul_f32 v[244:245], v[56:57], v[30:31] op_sel_hi:[1,0]
	v_pk_mul_f32 v[246:247], v[38:39], v[30:31] op_sel_hi:[1,0]
	v_pk_mul_f32 v[244:245], v[168:169], v[244:245]
	v_pk_mul_f32 v[246:247], v[170:171], v[246:247]
	v_cvt_pk_bf16_f32 v248, v244, v245
	v_cvt_pk_bf16_f32 v249, v246, v247
	global_store_dwordx2 v[28:29], v[248:249], off offset:96
	v_pk_mul_f32 v[244:245], v[44:45], v[30:31] op_sel_hi:[1,0]
	v_pk_mul_f32 v[246:247], v[34:35], v[30:31] op_sel_hi:[1,0]
	v_pk_mul_f32 v[244:245], v[172:173], v[244:245]
	v_pk_mul_f32 v[246:247], v[174:175], v[246:247]
	v_cvt_pk_bf16_f32 v250, v244, v245
	v_cvt_pk_bf16_f32 v251, v246, v247
	global_store_dwordx2 v[28:29], v[250:251], off offset:112
	v_pk_mul_f32 v[244:245], v[42:43], v[30:31] op_sel_hi:[1,0]
	v_pk_mul_f32 v[246:247], v[32:33], v[30:31] op_sel_hi:[1,0]
	v_pk_mul_f32 v[244:245], v[176:177], v[244:245]
	v_pk_mul_f32 v[246:247], v[178:179], v[246:247]
	v_cvt_pk_bf16_f32 v248, v244, v245
	v_cvt_pk_bf16_f32 v249, v246, v247
	global_store_dwordx2 v[28:29], v[248:249], off offset:128
	v_pk_mul_f32 v[244:245], v[40:41], v[30:31] op_sel_hi:[1,0]
	v_pk_mul_f32 v[246:247], v[22:23], v[30:31] op_sel_hi:[1,0]
	v_pk_mul_f32 v[244:245], v[180:181], v[244:245]
	v_pk_mul_f32 v[246:247], v[182:183], v[246:247]
	v_cvt_pk_bf16_f32 v250, v244, v245
	v_cvt_pk_bf16_f32 v251, v246, v247
	global_store_dwordx2 v[28:29], v[250:251], off offset:144
	v_pk_mul_f32 v[244:245], v[36:37], v[30:31] op_sel_hi:[1,0]
	v_pk_mul_f32 v[246:247], v[20:21], v[30:31] op_sel_hi:[1,0]
	v_pk_mul_f32 v[244:245], v[184:185], v[244:245]
	v_pk_mul_f32 v[246:247], v[186:187], v[246:247]
	v_cvt_pk_bf16_f32 v248, v244, v245
	v_cvt_pk_bf16_f32 v249, v246, v247
	global_store_dwordx2 v[28:29], v[248:249], off offset:160
	v_pk_mul_f32 v[244:245], v[26:27], v[30:31] op_sel_hi:[1,0]
	v_pk_mul_f32 v[246:247], v[18:19], v[30:31] op_sel_hi:[1,0]
	v_pk_mul_f32 v[244:245], v[188:189], v[244:245]
	v_pk_mul_f32 v[246:247], v[190:191], v[246:247]
	v_cvt_pk_bf16_f32 v250, v244, v245
	v_cvt_pk_bf16_f32 v251, v246, v247
	global_store_dwordx2 v[28:29], v[250:251], off offset:176
	v_pk_mul_f32 v[244:245], v[24:25], v[30:31] op_sel_hi:[1,0]
	v_pk_mul_f32 v[246:247], v[16:17], v[30:31] op_sel_hi:[1,0]
	v_pk_mul_f32 v[244:245], v[220:221], v[244:245]
	v_pk_mul_f32 v[246:247], v[222:223], v[246:247]
	v_cvt_pk_bf16_f32 v248, v244, v245
	v_cvt_pk_bf16_f32 v249, v246, v247
	global_store_dwordx2 v[28:29], v[248:249], off offset:192
	v_pk_mul_f32 v[244:245], v[6:7], v[30:31] op_sel_hi:[1,0]
	v_pk_mul_f32 v[246:247], v[2:3], v[30:31] op_sel_hi:[1,0]
	v_pk_mul_f32 v[244:245], v[224:225], v[244:245]
	v_pk_mul_f32 v[246:247], v[226:227], v[246:247]
	v_cvt_pk_bf16_f32 v250, v244, v245
	v_cvt_pk_bf16_f32 v251, v246, v247
	global_store_dwordx2 v[28:29], v[250:251], off offset:208
	v_pk_mul_f32 v[244:245], v[4:5], v[30:31] op_sel_hi:[1,0]
	v_pk_mul_f32 v[246:247], v[0:1], v[30:31] op_sel_hi:[1,0]
	v_pk_mul_f32 v[244:245], v[228:229], v[244:245]
	v_pk_mul_f32 v[246:247], v[230:231], v[246:247]
	v_cvt_pk_bf16_f32 v248, v244, v245
	v_cvt_pk_bf16_f32 v249, v246, v247
	global_store_dwordx2 v[28:29], v[248:249], off offset:224
	v_pk_mul_f32 v[244:245], v[64:65], v[30:31] op_sel_hi:[1,0]
	v_pk_mul_f32 v[246:247], v[66:67], v[30:31] op_sel_hi:[1,0]
	v_pk_mul_f32 v[244:245], v[232:233], v[244:245]
	v_pk_mul_f32 v[246:247], v[234:235], v[246:247]
	v_cvt_pk_bf16_f32 v250, v244, v245
	v_cvt_pk_bf16_f32 v251, v246, v247
	global_store_dwordx2 v[28:29], v[250:251], off offset:240
